# attention main loop: cross-half row-max exchange by v_permlane32_swap instead of ds_bpermute (on top of QK ring + staging interleave)
# baseline (speedup 1.0000x reference)
; #define LAS __attribute__((address_space(3)))
; __device__ __forceinline__ void attn_unit(const bf16* QB, const bf16* KN, const bf16* KR, const bf16* VT, bf16* YC, LAS unsigned char* lds, int b, int h, int u, int tid, int lane, int wave) {
;     ...
;         LAS unsigned char* st = lds + (kt & 1) * AT_STAGE;
;         if (kt < nt_wave) {
;             f32x16 sa[2];
; #pragma unroll
;             for (int mt = 0; mt < 2; ++mt) {
; #pragma unroll
;                 for (int i = 0; i < 16; ++i) sa[mt][i] = 0.f;
; #pragma unroll
;                 for (int ks = 0; ks < 12; ++ks) { const bf16x8 af = *(const LAS bf16x8*)(st + (32 * mt + r32) * AT_KSTR + 32 * ks + 16 * hi);
;                     sa[mt] = __builtin_amdgcn_mfma_f32_32x32x16_bf16(af, qf[ks], sa[mt], 0, 0, 0); }
;             }
;             float mx = sa[0][0];
; #pragma unroll
;             for (int i = 1; i < 16; ++i) mx = fmaxf(mx, sa[0][i]);
; #pragma unroll
;             for (int i = 0; i < 16; ++i) mx = fmaxf(mx, sa[1][i]);
;             mx = fmaxf(mx, __shfl_xor(mx, 32));
;             const bool grow = __builtin_amdgcn_ballot_w64(mx - m_run > 8.0f) != 0ull;
;             const float m_new = grow ? fmaxf(m_run, mx) : m_run; const float alpha = grow ? __builtin_amdgcn_exp2f(m_run - m_new) : 1.0f; m_run = m_new;
.LBB0_1470:
	s_add_i32 s6, s4, 1
	s_bitcmp1_b32 s6, 0
	s_cselect_b32 s5, 0xac00, 0
	s_add_i32 s28, s5, 0
	s_cmp_gt_i32 s4, s0
	s_cbranch_scc1 .Lattn_stage_only
	s_bitcmp1_b32 s4, 0
	s_cselect_b32 s4, 0xac00, 0
	v_add_u32_e32 v208, s4, v199
	v_add_u32_e32 v72, v208, v194
	v_add_u32_e32 v230, v208, v195
	ds_read_b128 v[210:213], v72
	ds_read_b128 v[214:217], v72 offset:32
	ds_read_b128 v[218:221], v72 offset:64
	ds_read_b128 v[222:225], v72 offset:96
	s_waitcnt lgkmcnt(3)
	v_mfma_f32_32x32x16_bf16 v[80:95], v[210:213], v[140:143], 0
	ds_read_b128 v[226:229], v72 offset:128
	v_add_u32_e32 v64, s28, v170
	s_waitcnt vmcnt(4)
	ds_write_b128 v64, v[148:151]
	s_waitcnt lgkmcnt(4)
	v_mfma_f32_32x32x16_bf16 v[80:95], v[214:217], v[136:139], v[80:95]
	ds_read_b128 v[210:213], v72 offset:160
	v_add_u32_e32 v64, s28, v174
	s_waitcnt vmcnt(3)
	ds_write_b128 v64, v[144:147] offset:25600
	s_waitcnt lgkmcnt(5)
	v_mfma_f32_32x32x16_bf16 v[80:95], v[218:221], v[132:135], v[80:95]
	ds_read_b128 v[214:217], v72 offset:192
	v_add_u32_e32 v64, s28, v172
	s_waitcnt vmcnt(2)
	ds_write_b128 v64, v[156:159]
	s_waitcnt lgkmcnt(6)
	v_mfma_f32_32x32x16_bf16 v[80:95], v[222:225], v[128:131], v[80:95]
	ds_read_b128 v[218:221], v72 offset:224
	v_add_u32_e32 v64, s28, v176
	s_waitcnt vmcnt(1)
	ds_write_b128 v64, v[152:155] offset:25600
	s_waitcnt lgkmcnt(7)
	v_mfma_f32_32x32x16_bf16 v[80:95], v[226:229], v[124:127], v[80:95]
	ds_read_b128 v[222:225], v72 offset:256
	v_add_u32_e32 v64, s28, v192
	s_waitcnt vmcnt(0)
	ds_write_b128 v64, v[160:163] offset:256
	s_waitcnt lgkmcnt(7)
	v_mfma_f32_32x32x16_bf16 v[80:95], v[210:213], v[120:123], v[80:95]
	ds_read_b128 v[226:229], v72 offset:288
	v_lshl_add_u64 v[64:65], v[168:169], 1, s[62:63]
	global_load_dwordx4 v[148:151], v[64:65], off
	s_waitcnt lgkmcnt(6)
	v_mfma_f32_32x32x16_bf16 v[80:95], v[214:217], v[116:119], v[80:95]
	ds_read_b128 v[210:213], v72 offset:320
	v_add_u32_e32 v66, v188, v207
	v_mov_b32_e32 v67, v169
	v_lshl_add_u64 v[66:67], v[66:67], 1, s[48:49]
	global_load_dwordx4 v[144:147], v[66:67], off
	s_waitcnt lgkmcnt(5)
	v_mfma_f32_32x32x16_bf16 v[80:95], v[218:221], v[112:115], v[80:95]
	ds_read_b128 v[214:217], v72 offset:352
	v_mov_b32_e32 v185, v169
	v_lshl_add_u64 v[64:65], v[184:185], 1, s[62:63]
	global_load_dwordx4 v[156:159], v[64:65], off
	s_waitcnt lgkmcnt(4)
	v_mfma_f32_32x32x16_bf16 v[80:95], v[222:225], v[108:111], v[80:95]
	ds_read_b128 v[218:221], v230
	v_add_u32_e32 v66, v188, v206
	v_mov_b32_e32 v67, v169
	v_lshl_add_u64 v[66:67], v[66:67], 1, s[48:49]
	global_load_dwordx4 v[152:155], v[66:67], off
	s_waitcnt lgkmcnt(3)
	v_mfma_f32_32x32x16_bf16 v[80:95], v[226:229], v[104:107], v[80:95]
	ds_read_b128 v[222:225], v230 offset:32
	v_add_u32_e32 v64, v188, v181
	v_mov_b32_e32 v65, v169
	v_lshl_add_u64 v[64:65], v[64:65], 1, s[54:55]
	global_load_dwordx4 v[160:163], v[64:65], off
	s_waitcnt lgkmcnt(3)
	v_mfma_f32_32x32x16_bf16 v[80:95], v[210:213], v[100:103], v[80:95]
	ds_read_b128 v[226:229], v230 offset:64
	s_waitcnt lgkmcnt(3)
	v_mfma_f32_32x32x16_bf16 v[80:95], v[214:217], v[96:99], v[80:95]
	ds_read_b128 v[210:213], v230 offset:96
	s_waitcnt lgkmcnt(3)
	v_mfma_f32_32x32x16_bf16 v[64:79], v[218:221], v[140:143], 0
	ds_read_b128 v[214:217], v230 offset:128
	s_waitcnt lgkmcnt(3)
	v_mfma_f32_32x32x16_bf16 v[64:79], v[222:225], v[136:139], v[64:79]
	ds_read_b128 v[218:221], v230 offset:160
	s_waitcnt lgkmcnt(3)
	v_mfma_f32_32x32x16_bf16 v[64:79], v[226:229], v[132:135], v[64:79]
	ds_read_b128 v[222:225], v230 offset:192
	s_waitcnt lgkmcnt(3)
	v_mfma_f32_32x32x16_bf16 v[64:79], v[210:213], v[128:131], v[64:79]
	ds_read_b128 v[226:229], v230 offset:224
	s_waitcnt lgkmcnt(3)
	v_mfma_f32_32x32x16_bf16 v[64:79], v[214:217], v[124:127], v[64:79]
	ds_read_b128 v[210:213], v230 offset:256
	v_max_f32_e32 v209, v80, v81
	v_max3_f32 v209, v209, v82, v83
	s_waitcnt lgkmcnt(3)
	v_mfma_f32_32x32x16_bf16 v[64:79], v[218:221], v[120:123], v[64:79]
	ds_read_b128 v[214:217], v230 offset:288
	v_max3_f32 v209, v209, v84, v85
	s_waitcnt lgkmcnt(3)
	v_mfma_f32_32x32x16_bf16 v[64:79], v[222:225], v[116:119], v[64:79]
	ds_read_b128 v[218:221], v230 offset:320
	v_max3_f32 v209, v209, v86, v87
	s_waitcnt lgkmcnt(3)
	v_mfma_f32_32x32x16_bf16 v[64:79], v[226:229], v[112:115], v[64:79]
	ds_read_b128 v[222:225], v230 offset:352
	v_max3_f32 v209, v209, v88, v89
	s_waitcnt lgkmcnt(3)
	v_mfma_f32_32x32x16_bf16 v[64:79], v[210:213], v[108:111], v[64:79]
	v_max3_f32 v209, v209, v90, v91
	s_waitcnt lgkmcnt(2)
	v_mfma_f32_32x32x16_bf16 v[64:79], v[214:217], v[104:107], v[64:79]
	v_max3_f32 v209, v209, v92, v93
	s_waitcnt lgkmcnt(1)
	v_mfma_f32_32x32x16_bf16 v[64:79], v[218:221], v[100:103], v[64:79]
	v_max3_f32 v209, v209, v94, v95
	s_waitcnt lgkmcnt(0)
	v_mfma_f32_32x32x16_bf16 v[64:79], v[222:225], v[96:99], v[64:79]
	s_nop 7
	s_nop 3
	v_max3_f32 v185, v209, v64, v65
	v_max3_f32 v185, v185, v66, v67
	v_max3_f32 v185, v185, v68, v69
	v_max3_f32 v185, v185, v70, v71
	v_max3_f32 v185, v185, v72, v73
	v_max3_f32 v185, v185, v74, v75
	v_max3_f32 v185, v185, v76, v77
	v_max3_f32 v185, v185, v78, v79
	v_mov_b32_e32 v209, v185
	s_nop 1
	v_permlane32_swap_b32_e32 v209, v185
	s_waitcnt lgkmcnt(0)
	v_max_f32_e32 v209, v209, v209
	v_max_f32_e32 v185, v185, v209
	v_sub_f32_e32 v209, v185, v186
	v_cmp_lt_f32_e32 vcc, s72, v209
	s_cmp_eq_u64 vcc, 0
	v_max_f32_e32 v209, v186, v186
	v_max_f32_e32 v185, v209, v185
	s_cselect_b64 s[4:5], -1, 0
	v_cndmask_b32_e64 v185, v185, v186, s[4:5]
	v_sub_f32_e32 v186, v186, v185
	v_exp_f32_e32 v186, v186
	s_and_b64 vcc, exec, s[4:5]
	s_cbranch_vccnz .LBB0_1473
; __device__ __forceinline__ void attn_unit(const bf16* QB, const bf16* KN, const bf16* KR, const bf16* VT, bf16* YC, LAS unsigned char* lds, int b, int h, int u, int tid, int lane, int wave) {
;     ...
;             if (grow) {
; #pragma unroll
;                 for (int d = 0; d < 4; ++d)
; #pragma unroll
;                     for (int i = 0; i < 16; ++i) ot[d][i] *= alpha;
;             }
	v_pk_mul_f32 v[62:63], v[62:63], v[186:187] op_sel_hi:[1,0]
	v_pk_mul_f32 v[60:61], v[60:61], v[186:187] op_sel_hi:[1,0]
	v_pk_mul_f32 v[58:59], v[58:59], v[186:187] op_sel_hi:[1,0]
	v_pk_mul_f32 v[56:57], v[56:57], v[186:187] op_sel_hi:[1,0]
	v_pk_mul_f32 v[54:55], v[54:55], v[186:187] op_sel_hi:[1,0]
	v_pk_mul_f32 v[52:53], v[52:53], v[186:187] op_sel_hi:[1,0]
	v_pk_mul_f32 v[50:51], v[50:51], v[186:187] op_sel_hi:[1,0]
	v_pk_mul_f32 v[48:49], v[48:49], v[186:187] op_sel_hi:[1,0]
	v_pk_mul_f32 v[46:47], v[46:47], v[186:187] op_sel_hi:[1,0]
	v_pk_mul_f32 v[44:45], v[44:45], v[186:187] op_sel_hi:[1,0]
	v_pk_mul_f32 v[42:43], v[42:43], v[186:187] op_sel_hi:[1,0]
	v_pk_mul_f32 v[40:41], v[40:41], v[186:187] op_sel_hi:[1,0]
	v_pk_mul_f32 v[38:39], v[38:39], v[186:187] op_sel_hi:[1,0]
	v_pk_mul_f32 v[36:37], v[36:37], v[186:187] op_sel_hi:[1,0]
	v_pk_mul_f32 v[34:35], v[34:35], v[186:187] op_sel_hi:[1,0]
	v_pk_mul_f32 v[32:33], v[32:33], v[186:187] op_sel_hi:[1,0]
	v_pk_mul_f32 v[30:31], v[30:31], v[186:187] op_sel_hi:[1,0]
	v_pk_mul_f32 v[28:29], v[28:29], v[186:187] op_sel_hi:[1,0]
	v_pk_mul_f32 v[26:27], v[26:27], v[186:187] op_sel_hi:[1,0]
	v_pk_mul_f32 v[24:25], v[24:25], v[186:187] op_sel_hi:[1,0]
	v_pk_mul_f32 v[22:23], v[22:23], v[186:187] op_sel_hi:[1,0]
	v_pk_mul_f32 v[20:21], v[20:21], v[186:187] op_sel_hi:[1,0]
	v_pk_mul_f32 v[18:19], v[18:19], v[186:187] op_sel_hi:[1,0]
	v_pk_mul_f32 v[16:17], v[16:17], v[186:187] op_sel_hi:[1,0]
	v_pk_mul_f32 v[14:15], v[14:15], v[186:187] op_sel_hi:[1,0]
	v_pk_mul_f32 v[12:13], v[12:13], v[186:187] op_sel_hi:[1,0]
	v_pk_mul_f32 v[10:11], v[10:11], v[186:187] op_sel_hi:[1,0]
	v_pk_mul_f32 v[8:9], v[8:9], v[186:187] op_sel_hi:[1,0]
	v_pk_mul_f32 v[6:7], v[6:7], v[186:187] op_sel_hi:[1,0]
	v_pk_mul_f32 v[4:5], v[4:5], v[186:187] op_sel_hi:[1,0]
	v_pk_mul_f32 v[2:3], v[2:3], v[186:187] op_sel_hi:[1,0]
	v_pk_mul_f32 v[0:1], v[0:1], v[186:187] op_sel_hi:[1,0]
